# byte-placement trial: merge phase code shifted by 48 bytes (M K-loop head at offset 32 of a 64-byte line), code after the phase kept in place
# baseline (speedup 1.0000x reference)
; template <int MB, bool PF2 = true>
; DI void gemm_main(const u16* __restrict__ A, int lda, const u16* __restrict__ B, int ldb, int K, f32x16 (&acc)[MB][2], GemmLds* s, int tid) {
;   const int lane = tid & 63, w = tid >> 6, r = lane & 31, h = lane >> 5, wm = w >> 1, wn = w & 1;
;   const int srow = tid >> 3, skc = (tid & 7) * 8;
;   const unsigned oa0 = (unsigned)(srow * lda + skc) * 2u, oa1 = oa0 + 64u * lda, oa2 = oa0 + 128u * lda, oa3 = oa0 + 192u * lda;
;   const unsigned ob0 = (unsigned)(srow * ldb + skc) * 2u, ob1 = ob0 + 64u * ldb, ob2 = ob0 + 128u * ldb, ob3 = ob0 + 192u * ldb;
; DI void phase_merge(const Params& p, int l, char* smem, int tid) {
;   const int lane = tid & 63, w = tid >> 6, r = lane & 31, h = lane >> 5, wm = w >> 1, wn = w & 1;
;   GemmLds* s = (GemmLds*)smem;
;   u16* ACC = p.Pk;
;   const bool dyn = (l == 0);
;   unsigned* qc = p.bar + 4096 + 320;
;   for (int it = (dyn ? fetch_item(qc, smem) : (int)blockIdx.x); it < 544 * 8; it = (dyn ? fetch_item(qc, smem) : it + (int)gridDim.x)) {
.LBB0_1140:
	s_or_b64 exec, exec, s[0:1]
	v_readlane_b32 s2, v254, 17
	v_readlane_b32 s3, v254, 18
	v_mov_b32_e32 v0, v206
	s_andn2_b64 vcc, exec, s[2:3]
	v_cndmask_b32_e64 v2, 0, 1, s[2:3]
	v_cmp_ne_u32_e64 s[0:1], 1, v2
	v_mov_b32_e32 v149, s48
	s_waitcnt lgkmcnt(0)
	s_barrier
	v_readlane_b32 s18, v254, 19
	v_and_b32_e32 v147, 63, v206
	v_lshrrev_b32_e32 v149, 6, v206
	v_lshrrev_b32_e32 v151, 3, v147
	v_lshl_add_u32 v151, v149, 5, v151
	v_lshlrev_b32_e32 v151, 11, v151
	v_and_b32_e32 v153, 7, v147
	v_lshrrev_b32_e32 v147, 4, v147
	v_xor_b32_e32 v153, v153, v147
	v_lshl_or_b32 v200, v153, 4, v151
	v_xor_b32_e32 v201, 64, v200
	v_add_u32_e32 v201, 16384, v201
	v_add_u32_e32 v202, 32768, v200
	v_add_u32_e32 v203, 32768, v201
	v_and_b32_e32 v147, 63, v206
	v_lshrrev_b32_e32 v149, 6, v206
	v_lshrrev_b32_e32 v151, 3, v147
	v_lshl_add_u32 v151, v149, 5, v151
	v_lshlrev_b32_e32 v151, 9, v151
	v_and_b32_e32 v153, 7, v147
	v_lshrrev_b32_e32 v147, 4, v147
	v_xor_b32_e32 v153, v153, v147
	v_lshl_or_b32 v130, v153, 4, v151
	v_xor_b32_e32 v131, 64, v130
	v_add_u32_e32 v131, 4096, v131
	v_add_u32_e32 v132, 8192, v130
	v_add_u32_e32 v133, 8192, v131
	v_lshrrev_b32_e32 v204, 6, v206
	v_and_b32_e32 v147, 31, v206
	v_bfe_u32 v149, v206, 5, 1
	v_bfe_u32 v151, v147, 1, 3
	v_xor_b32_e32 v151, v151, v149
	v_lshlrev_b32_e32 v151, 4, v151
	v_lshl_or_b32 v151, v147, 7, v151
	v_lshrrev_b32_e32 v153, 7, v206
	v_lshl_add_u32 v138, v153, 13, v151
	v_bfe_u32 v153, v206, 6, 1
	v_lshl_add_u32 v142, v153, 13, v151
	v_add_u32_e32 v142, 0x4000, v142
	v_xor_b32_e32 v139, 32, v138
	v_xor_b32_e32 v143, 32, v142
	v_xor_b32_e32 v140, 64, v138
	v_xor_b32_e32 v144, 64, v142
	v_xor_b32_e32 v141, 96, v138
	v_xor_b32_e32 v145, 96, v142
	v_and_b32_e32 v147, 31, v206
	v_lshrrev_b32_e32 v149, 7, v206
	v_lshl_add_u32 v147, v149, 6, v147
	v_lshlrev_b32_e32 v147, 11, v147
	v_bfe_u32 v149, v206, 6, 1
	v_lshlrev_b32_e32 v149, 7, v149
	v_bfe_u32 v151, v206, 5, 1
	v_lshl_or_b32 v149, v151, 3, v149
	v_or_b32_e32 v146, v147, v149
	v_lshrrev_b32_e32 v147, 6, v206
	v_mul_u32_u24_e32 v147, 0x2400, v147
	v_and_b32_e32 v149, 31, v206
	v_mul_u32_u24_e32 v149, 0x90, v149
	v_bfe_u32 v151, v206, 5, 1
	v_lshl_add_u32 v149, v151, 3, v149
	v_add_u32_e32 v134, v147, v149
	v_bfe_u32 v149, v206, 3, 3
	v_mul_u32_u24_e32 v149, 0x90, v149
	v_and_b32_e32 v151, 7, v206
	v_lshl_add_u32 v149, v151, 4, v149
	v_add_u32_e32 v135, v147, v149
	v_bfe_u32 v147, v206, 3, 3
	v_lshrrev_b32_e32 v149, 7, v206
	v_lshl_add_u32 v147, v149, 6, v147
	v_mul_u32_u24_e32 v147, 0x800, v147
	v_bfe_u32 v149, v206, 6, 1
	v_lshlrev_b32_e32 v149, 7, v149
	v_and_b32_e32 v151, 7, v206
	v_lshl_or_b32 v149, v151, 4, v149
	v_add_u32_e32 v136, v147, v149
	v_readfirstlane_b32 s10, v204
	s_lshl_b32 s10, s10, 12
	s_lshl_b32 s6, s18, 23
	s_add_u32 s14, s96, 0x1b720000
	s_addc_u32 s15, s97, 0
	s_add_u32 s14, s14, s6
	s_addc_u32 s15, s15, 0
	s_lshl_b32 s6, s18, 21
	s_add_u32 s16, s96, 0x1c800000
	s_addc_u32 s17, s97, 0
	s_add_u32 s16, s16, s6
	s_addc_u32 s17, s17, 0
	s_mov_b32 s12, s48
	s_nop 0
	s_nop 0
	s_nop 0
	s_nop 0
	s_nop 0
	s_nop 0
	s_nop 0
	s_nop 0
	s_nop 0
	s_nop 0
	s_nop 0
	s_nop 0

; DI int launder_i(int v) { asm volatile("" : "+v"(v)); return v; }
; #define GRID_BAR() xcd_barrier((unsigned*)(ka.ws + OFF_BAR), xb_xcc_id(), (volatile unsigned*)&xb_words)
; DI void xcd_barrier(unsigned* bar, unsigned x, volatile unsigned* st) {
;   asm volatile("s_waitcnt vmcnt(0)" ::: "memory");
;   __syncthreads();
; __global__ void __launch_bounds__(256, 2) mega_kernel(KArgs ka) {
;     ...
;     { Params p = make_params(ka); phase_merge(p, l, smem, launder_i(tid)); } GRID_BAR();
.Lmg_done:
	s_nop 0
	s_nop 0
	s_nop 0
	s_nop 0
	s_waitcnt vmcnt(0) lgkmcnt(0)
